# GEMM K-loop: weight (B operand) LDS-DMA loads marked nt (on v37)
# baseline (speedup 1.0000x reference)
; #define PG8_STAGE(bufoff, gbase, voff) do { _Pragma("unroll") for (int _i = 0; _i < 2; ++_i) \
;         __builtin_amdgcn_global_load_lds((const unsigned*)((const char*)(gbase) + (voff)[_i]), (PG8_LAS unsigned*)(lds + (bufoff) + ldsw + _i * 8192), 16, 0, 0); } while (0)
; #define PG8_LDA(dst, b, h) do { _Pragma("unroll") for (int m = 0; m < 4; ++m) _Pragma("unroll") for (int k = 0; k < 2; ++k) dst[m][k] = *(const PG8_LAS bf16x8*)(lds + PG8_SA(b, h) + aoff + m * 2048 + k * 1024); } while (0)
; #define PG8_LDB(dst, b, h) do { _Pragma("unroll") for (int n = 0; n < 2; ++n) _Pragma("unroll") for (int k = 0; k < 2; ++k) dst[n][k] = *(const PG8_LAS bf16x8*)(lds + PG8_SB(b, h) + boff + n * 2048 + k * 1024); } while (0)
; #define PG8_MMA(ai, bj, At, Bt) do { __builtin_amdgcn_s_setprio(1); _Pragma("unroll") for (int m = 0; m < 4; ++m) _Pragma("unroll") for (int n = 0; n < 2; ++n) _Pragma("unroll") for (int k = 0; k < 2; ++k) \
;         acc[ai][bj][m][n] = __builtin_amdgcn_mfma_f32_16x16x32_bf16(Bt[n][k], At[m][k], acc[ai][bj][m][n], 0, 0, 0); __builtin_amdgcn_s_setprio(0); } while (0)
; #define PG8_WAIT_V(n) asm volatile("s_waitcnt vmcnt(" #n ")" ::: "memory")
; #define PG8_WAIT_L(n) asm volatile("s_waitcnt lgkmcnt(" #n ")" ::: "memory")
; #define PG8_BAR __builtin_amdgcn_s_barrier()
; #define PG8_SCHED __builtin_amdgcn_sched_barrier(0)
; template <class Epi, class Sched, bool ALIGN_EPI = false, bool SP2 = false>
; __device__ __forceinline__ void gemm_phase(PG8_LAS unsigned char* lds, const Gemm g, const Sched& S, const Epi& E) {
;     ...
;             PG8_LDB(B0, 0, 0); PG8_LDB(B1, 0, 1); PG8_SCHED; PG8_LDA(At, 0, 0); PG8_STAGE(PG8_SA(1, 1), a1 + hstepB, voffA);
;             PG8_WAIT_V(8); PG8_WAIT_L(0); PG8_BAR; PG8_MMA(0, 0, At, B0); PG8_MMA(0, 1, At, B1); PG8_BAR; PG8_SCHED;
;             PG8_LDA(At, 0, 1); PG8_STAGE(PG8_SB(0, 0), b2, voffB); PG8_STAGE(PG8_SB(0, 1), b2 + hstepB, voffB); PG8_STAGE(PG8_SA(0, 0), a2, voffA);
;             PG8_WAIT_V(8); PG8_WAIT_L(0); PG8_BAR; PG8_MMA(1, 0, At, B0); PG8_MMA(1, 1, At, B1); PG8_BAR; PG8_SCHED;
.LBB0_372:
	s_add_i32 s71, s71, 2
	s_add_u32 s12, s6, 0x1fc000
	s_addc_u32 s13, s7, 0
	s_and_b64 s[26:27], exec, s[26:27]
	s_cselect_b32 s26, s69, s12
	s_cselect_b32 s27, s59, s13
	s_add_u32 vcc_lo, s26, 0x200000
	s_addc_u32 vcc_hi, s27, 0
	s_add_i32 s12, 0, 0x10000
	v_add_u32_e32 v142, s12, v144
	s_add_i32 s73, 0, 0x14000
	ds_read_b128 v[148:151], v142
	ds_read_b128 v[152:155], v142 offset:1024
	ds_read_b128 v[156:159], v142 offset:2048
	ds_read_b128 v[160:163], v142 offset:3072
	v_add_u32_e32 v142, s73, v144
	ds_read_b128 v[164:167], v142
	ds_read_b128 v[168:171], v142 offset:1024
	ds_read_b128 v[172:175], v142 offset:2048
	ds_read_b128 v[176:179], v142 offset:3072
	v_lshl_add_u64 v[142:143], s[6:7], 0, v[138:139]
	s_add_i32 m0, s45, 0xc000
	ds_read_b128 v[180:183], v146
	ds_read_b128 v[184:187], v146 offset:1024
	ds_read_b128 v[188:191], v146 offset:2048
	ds_read_b128 v[192:195], v146 offset:3072
	ds_read_b128 v[196:199], v146 offset:4096
	ds_read_b128 v[200:203], v146 offset:5120
	ds_read_b128 v[204:207], v146 offset:6144
	ds_read_b128 v[222:225], v146 offset:7168
	global_load_lds_dwordx4 v[142:143], off
	v_lshl_add_u64 v[142:143], s[6:7], 0, v[140:141]
	s_add_i32 m0, s45, 0xe000
	s_nop 0
	global_load_lds_dwordx4 v[142:143], off
	s_waitcnt vmcnt(8)
	s_waitcnt lgkmcnt(0)
	s_barrier
	s_setprio 1
	s_waitcnt lgkmcnt(0)
	v_mfma_f32_16x16x32_bf16 v[126:129], v[148:151], v[180:183], v[126:129]
	v_mfma_f32_16x16x32_bf16 v[122:125], v[156:159], v[180:183], v[122:125]
	v_mfma_f32_16x16x32_bf16 v[114:117], v[148:151], v[188:191], v[114:117]
	v_mfma_f32_16x16x32_bf16 v[106:109], v[156:159], v[188:191], v[106:109]
	v_mfma_f32_16x16x32_bf16 v[98:101], v[148:151], v[196:199], v[98:101]
	v_mfma_f32_16x16x32_bf16 v[90:93], v[156:159], v[196:199], v[90:93]
	v_mfma_f32_16x16x32_bf16 v[82:85], v[148:151], v[204:207], v[82:85]
	v_mfma_f32_16x16x32_bf16 v[74:77], v[156:159], v[204:207], v[74:77]
	v_mfma_f32_16x16x32_bf16 v[126:129], v[152:155], v[184:187], v[126:129]
	v_mfma_f32_16x16x32_bf16 v[122:125], v[160:163], v[184:187], v[122:125]
	v_mfma_f32_16x16x32_bf16 v[114:117], v[152:155], v[192:195], v[114:117]
	v_mfma_f32_16x16x32_bf16 v[106:109], v[160:163], v[192:195], v[106:109]
	v_mfma_f32_16x16x32_bf16 v[98:101], v[152:155], v[200:203], v[98:101]
	v_mfma_f32_16x16x32_bf16 v[90:93], v[160:163], v[200:203], v[90:93]
	v_mfma_f32_16x16x32_bf16 v[82:85], v[152:155], v[222:225], v[82:85]
	v_mfma_f32_16x16x32_bf16 v[74:77], v[160:163], v[222:225], v[74:77]
	s_setprio 0
	s_setprio 1
	v_mfma_f32_16x16x32_bf16 v[118:121], v[164:167], v[180:183], v[118:121]
	v_mfma_f32_16x16x32_bf16 v[110:113], v[172:175], v[180:183], v[110:113]
	v_mfma_f32_16x16x32_bf16 v[102:105], v[164:167], v[188:191], v[102:105]
	v_mfma_f32_16x16x32_bf16 v[94:97], v[172:175], v[188:191], v[94:97]
	v_mfma_f32_16x16x32_bf16 v[86:89], v[164:167], v[196:199], v[86:89]
	v_mfma_f32_16x16x32_bf16 v[78:81], v[172:175], v[196:199], v[78:81]
	v_mfma_f32_16x16x32_bf16 v[70:73], v[164:167], v[204:207], v[70:73]
	v_mfma_f32_16x16x32_bf16 v[66:69], v[172:175], v[204:207], v[66:69]
	v_mfma_f32_16x16x32_bf16 v[118:121], v[168:171], v[184:187], v[118:121]
	v_mfma_f32_16x16x32_bf16 v[110:113], v[176:179], v[184:187], v[110:113]
	v_mfma_f32_16x16x32_bf16 v[102:105], v[168:171], v[192:195], v[102:105]
	v_mfma_f32_16x16x32_bf16 v[94:97], v[176:179], v[192:195], v[94:97]
	v_mfma_f32_16x16x32_bf16 v[86:89], v[168:171], v[200:203], v[86:89]
	v_mfma_f32_16x16x32_bf16 v[78:81], v[176:179], v[200:203], v[78:81]
	v_mfma_f32_16x16x32_bf16 v[70:73], v[168:171], v[222:225], v[70:73]
	v_mfma_f32_16x16x32_bf16 v[66:69], v[176:179], v[222:225], v[66:69]
	s_setprio 0
	s_barrier
	s_add_i32 s12, s12, s23
	v_lshl_add_u64 v[142:143], s[74:75], 0, v[134:135]
	s_mov_b32 m0, s12
	ds_read_b128 v[180:183], v146 offset:16384
	ds_read_b128 v[184:187], v146 offset:17408
	ds_read_b128 v[188:191], v146 offset:18432
	ds_read_b128 v[192:195], v146 offset:19456
	ds_read_b128 v[196:199], v146 offset:20480
	ds_read_b128 v[200:203], v146 offset:21504
	ds_read_b128 v[204:207], v146 offset:22528
	ds_read_b128 v[222:225], v146 offset:23552
	global_load_lds_dwordx4 v[142:143], off nt
	s_add_i32 m0, s12, 0x2000
	s_add_u32 s12, s74, 0x4000
	v_lshl_add_u64 v[142:143], s[74:75], 0, v[130:131]
	s_addc_u32 s13, s75, 0
	s_add_i32 s73, s73, s23
	global_load_lds_dwordx4 v[142:143], off nt
	v_lshl_add_u64 v[142:143], s[12:13], 0, v[134:135]
	s_mov_b32 m0, s73
	s_nop 0
	global_load_lds_dwordx4 v[142:143], off nt
	v_lshl_add_u64 v[142:143], s[12:13], 0, v[130:131]
	s_add_i32 m0, s73, 0x2000
	s_nop 0
	global_load_lds_dwordx4 v[142:143], off nt
	v_lshl_add_u64 v[142:143], s[26:27], 0, v[136:137]
	s_mov_b32 m0, s45
	s_nop 0
	global_load_lds_dwordx4 v[142:143], off
	v_lshl_add_u64 v[142:143], s[26:27], 0, v[132:133]
	s_mov_b32 m0, s49
	s_nop 0
	global_load_lds_dwordx4 v[142:143], off
	s_waitcnt vmcnt(8)
	s_waitcnt lgkmcnt(0)
	s_barrier
; #define PG8_STAGE(bufoff, gbase, voff) do { _Pragma("unroll") for (int _i = 0; _i < 2; ++_i) \
;         __builtin_amdgcn_global_load_lds((const unsigned*)((const char*)(gbase) + (voff)[_i]), (PG8_LAS unsigned*)(lds + (bufoff) + ldsw + _i * 8192), 16, 0, 0); } while (0)
; #define PG8_LDA(dst, b, h) do { _Pragma("unroll") for (int m = 0; m < 4; ++m) _Pragma("unroll") for (int k = 0; k < 2; ++k) dst[m][k] = *(const PG8_LAS bf16x8*)(lds + PG8_SA(b, h) + aoff + m * 2048 + k * 1024); } while (0)
; #define PG8_LDB(dst, b, h) do { _Pragma("unroll") for (int n = 0; n < 2; ++n) _Pragma("unroll") for (int k = 0; k < 2; ++k) dst[n][k] = *(const PG8_LAS bf16x8*)(lds + PG8_SB(b, h) + boff + n * 2048 + k * 1024); } while (0)
; #define PG8_MMA(ai, bj, At, Bt) do { __builtin_amdgcn_s_setprio(1); _Pragma("unroll") for (int m = 0; m < 4; ++m) _Pragma("unroll") for (int n = 0; n < 2; ++n) _Pragma("unroll") for (int k = 0; k < 2; ++k) \
;         acc[ai][bj][m][n] = __builtin_amdgcn_mfma_f32_16x16x32_bf16(Bt[n][k], At[m][k], acc[ai][bj][m][n], 0, 0, 0); __builtin_amdgcn_s_setprio(0); } while (0)
; #define PG8_WAIT_V(n) asm volatile("s_waitcnt vmcnt(" #n ")" ::: "memory")
; #define PG8_WAIT_L(n) asm volatile("s_waitcnt lgkmcnt(" #n ")" ::: "memory")
; #define PG8_BAR __builtin_amdgcn_s_barrier()
; #define PG8_SCHED __builtin_amdgcn_sched_barrier(0)
; template <class Epi, class Sched, bool ALIGN_EPI = false, bool SP2 = false>
; __device__ __forceinline__ void gemm_phase(PG8_LAS unsigned char* lds, const Gemm g, const Sched& S, const Epi& E) {
;     ...
;             PG8_WAIT_V(8); PG8_WAIT_L(0); PG8_BAR; PG8_MMA(1, 0, At, B0); PG8_MMA(1, 1, At, B1); PG8_BAR; PG8_SCHED;
;             PG8_LDB(B0, 1, 0); PG8_LDB(B1, 1, 1); PG8_SCHED; PG8_LDA(At, 1, 0); PG8_STAGE(PG8_SA(0, 1), a2 + hstepB, voffA);
;             PG8_WAIT_V(8); PG8_WAIT_L(0); PG8_BAR; PG8_MMA(0, 0, At, B0); PG8_MMA(0, 1, At, B1); PG8_BAR; PG8_SCHED;
	s_setprio 1
	s_waitcnt lgkmcnt(0)
	v_mfma_f32_16x16x32_bf16 v[62:65], v[148:151], v[180:183], v[62:65]
	v_mfma_f32_16x16x32_bf16 v[58:61], v[156:159], v[180:183], v[58:61]
	v_mfma_f32_16x16x32_bf16 v[46:49], v[148:151], v[188:191], v[46:49]
	v_mfma_f32_16x16x32_bf16 v[42:45], v[156:159], v[188:191], v[42:45]
	v_mfma_f32_16x16x32_bf16 v[30:33], v[148:151], v[196:199], v[30:33]
	v_mfma_f32_16x16x32_bf16 v[26:29], v[156:159], v[196:199], v[26:29]
	v_mfma_f32_16x16x32_bf16 v[14:17], v[148:151], v[204:207], v[14:17]
	v_mfma_f32_16x16x32_bf16 v[10:13], v[156:159], v[204:207], v[10:13]
	v_mfma_f32_16x16x32_bf16 v[62:65], v[152:155], v[184:187], v[62:65]
	v_mfma_f32_16x16x32_bf16 v[58:61], v[160:163], v[184:187], v[58:61]
	v_mfma_f32_16x16x32_bf16 v[46:49], v[152:155], v[192:195], v[46:49]
	v_mfma_f32_16x16x32_bf16 v[42:45], v[160:163], v[192:195], v[42:45]
	v_mfma_f32_16x16x32_bf16 v[30:33], v[152:155], v[200:203], v[30:33]
	v_mfma_f32_16x16x32_bf16 v[26:29], v[160:163], v[200:203], v[26:29]
	v_mfma_f32_16x16x32_bf16 v[14:17], v[152:155], v[222:225], v[14:17]
	v_mfma_f32_16x16x32_bf16 v[10:13], v[160:163], v[222:225], v[10:13]
	s_setprio 0
	s_setprio 1
	v_mfma_f32_16x16x32_bf16 v[54:57], v[164:167], v[180:183], v[54:57]
	v_mfma_f32_16x16x32_bf16 v[50:53], v[172:175], v[180:183], v[50:53]
	v_mfma_f32_16x16x32_bf16 v[38:41], v[164:167], v[188:191], v[38:41]
	v_mfma_f32_16x16x32_bf16 v[34:37], v[172:175], v[188:191], v[34:37]
	v_mfma_f32_16x16x32_bf16 v[22:25], v[164:167], v[196:199], v[22:25]
	v_mfma_f32_16x16x32_bf16 v[18:21], v[172:175], v[196:199], v[18:21]
	v_mfma_f32_16x16x32_bf16 v[6:9], v[164:167], v[204:207], v[6:9]
	v_mfma_f32_16x16x32_bf16 v[2:5], v[172:175], v[204:207], v[2:5]
	v_mfma_f32_16x16x32_bf16 v[54:57], v[168:171], v[184:187], v[54:57]
	v_mfma_f32_16x16x32_bf16 v[50:53], v[176:179], v[184:187], v[50:53]
	v_mfma_f32_16x16x32_bf16 v[38:41], v[168:171], v[192:195], v[38:41]
	v_mfma_f32_16x16x32_bf16 v[34:37], v[176:179], v[192:195], v[34:37]
	v_mfma_f32_16x16x32_bf16 v[22:25], v[168:171], v[200:203], v[22:25]
	v_mfma_f32_16x16x32_bf16 v[18:21], v[176:179], v[200:203], v[18:21]
	v_mfma_f32_16x16x32_bf16 v[6:9], v[168:171], v[222:225], v[6:9]
	v_mfma_f32_16x16x32_bf16 v[2:5], v[176:179], v[222:225], v[2:5]
	s_setprio 0
	s_barrier
	s_add_i32 s73, 0, 0x18000
	v_add_u32_e32 v142, s73, v144
	s_add_i32 s61, 0, 0x1c000
	ds_read_b128 v[148:151], v142
	ds_read_b128 v[152:155], v142 offset:1024
	ds_read_b128 v[156:159], v142 offset:2048
	ds_read_b128 v[160:163], v142 offset:3072
	v_add_u32_e32 v142, s61, v144
	ds_read_b128 v[164:167], v142
	ds_read_b128 v[168:171], v142 offset:1024
	ds_read_b128 v[172:175], v142 offset:2048
	ds_read_b128 v[176:179], v142 offset:3072
	s_add_u32 s12, s26, 0x4000
	s_addc_u32 s13, s27, 0
	s_mov_b32 m0, s52
	v_lshl_add_u64 v[142:143], s[12:13], 0, v[136:137]
	ds_read_b128 v[180:183], v146 offset:32768
	ds_read_b128 v[184:187], v146 offset:33792
	ds_read_b128 v[188:191], v146 offset:34816
	ds_read_b128 v[192:195], v146 offset:35840
	ds_read_b128 v[196:199], v146 offset:36864
	ds_read_b128 v[200:203], v146 offset:37888
	ds_read_b128 v[204:207], v146 offset:38912
	ds_read_b128 v[222:225], v146 offset:39936
	global_load_lds_dwordx4 v[142:143], off
	v_lshl_add_u64 v[142:143], s[12:13], 0, v[132:133]
	s_mov_b32 m0, s53
	s_nop 0
	global_load_lds_dwordx4 v[142:143], off
	s_waitcnt vmcnt(8)
	s_waitcnt lgkmcnt(0)
	s_barrier
	s_setprio 1
	s_waitcnt lgkmcnt(0)
	v_mfma_f32_16x16x32_bf16 v[126:129], v[148:151], v[180:183], v[126:129]
	v_mfma_f32_16x16x32_bf16 v[122:125], v[156:159], v[180:183], v[122:125]
	v_mfma_f32_16x16x32_bf16 v[114:117], v[148:151], v[188:191], v[114:117]
	v_mfma_f32_16x16x32_bf16 v[106:109], v[156:159], v[188:191], v[106:109]
	v_mfma_f32_16x16x32_bf16 v[98:101], v[148:151], v[196:199], v[98:101]
	v_mfma_f32_16x16x32_bf16 v[90:93], v[156:159], v[196:199], v[90:93]
	v_mfma_f32_16x16x32_bf16 v[82:85], v[148:151], v[204:207], v[82:85]
	v_mfma_f32_16x16x32_bf16 v[74:77], v[156:159], v[204:207], v[74:77]
	v_mfma_f32_16x16x32_bf16 v[126:129], v[152:155], v[184:187], v[126:129]
	v_mfma_f32_16x16x32_bf16 v[122:125], v[160:163], v[184:187], v[122:125]
	v_mfma_f32_16x16x32_bf16 v[114:117], v[152:155], v[192:195], v[114:117]
	v_mfma_f32_16x16x32_bf16 v[106:109], v[160:163], v[192:195], v[106:109]
	v_mfma_f32_16x16x32_bf16 v[98:101], v[152:155], v[200:203], v[98:101]
	v_mfma_f32_16x16x32_bf16 v[90:93], v[160:163], v[200:203], v[90:93]
	v_mfma_f32_16x16x32_bf16 v[82:85], v[152:155], v[222:225], v[82:85]
	v_mfma_f32_16x16x32_bf16 v[74:77], v[160:163], v[222:225], v[74:77]
	s_setprio 0
	s_setprio 1
	v_mfma_f32_16x16x32_bf16 v[118:121], v[164:167], v[180:183], v[118:121]
	v_mfma_f32_16x16x32_bf16 v[110:113], v[172:175], v[180:183], v[110:113]
	v_mfma_f32_16x16x32_bf16 v[102:105], v[164:167], v[188:191], v[102:105]
	v_mfma_f32_16x16x32_bf16 v[94:97], v[172:175], v[188:191], v[94:97]
	v_mfma_f32_16x16x32_bf16 v[86:89], v[164:167], v[196:199], v[86:89]
	v_mfma_f32_16x16x32_bf16 v[78:81], v[172:175], v[196:199], v[78:81]
	v_mfma_f32_16x16x32_bf16 v[70:73], v[164:167], v[204:207], v[70:73]
	v_mfma_f32_16x16x32_bf16 v[66:69], v[172:175], v[204:207], v[66:69]
	v_mfma_f32_16x16x32_bf16 v[118:121], v[168:171], v[184:187], v[118:121]
	v_mfma_f32_16x16x32_bf16 v[110:113], v[176:179], v[184:187], v[110:113]
	v_mfma_f32_16x16x32_bf16 v[102:105], v[168:171], v[192:195], v[102:105]
	v_mfma_f32_16x16x32_bf16 v[94:97], v[176:179], v[192:195], v[94:97]
	v_mfma_f32_16x16x32_bf16 v[86:89], v[168:171], v[200:203], v[86:89]
	v_mfma_f32_16x16x32_bf16 v[78:81], v[176:179], v[200:203], v[78:81]
	v_mfma_f32_16x16x32_bf16 v[70:73], v[168:171], v[222:225], v[70:73]
	v_mfma_f32_16x16x32_bf16 v[66:69], v[176:179], v[222:225], v[66:69]
	s_setprio 0
	s_barrier
; #define PG8_STAGE(bufoff, gbase, voff) do { _Pragma("unroll") for (int _i = 0; _i < 2; ++_i) \
;         __builtin_amdgcn_global_load_lds((const unsigned*)((const char*)(gbase) + (voff)[_i]), (PG8_LAS unsigned*)(lds + (bufoff) + ldsw + _i * 8192), 16, 0, 0); } while (0)
; #define PG8_LDA(dst, b, h) do { _Pragma("unroll") for (int m = 0; m < 4; ++m) _Pragma("unroll") for (int k = 0; k < 2; ++k) dst[m][k] = *(const PG8_LAS bf16x8*)(lds + PG8_SA(b, h) + aoff + m * 2048 + k * 1024); } while (0)
; #define PG8_MMA(ai, bj, At, Bt) do { __builtin_amdgcn_s_setprio(1); _Pragma("unroll") for (int m = 0; m < 4; ++m) _Pragma("unroll") for (int n = 0; n < 2; ++n) _Pragma("unroll") for (int k = 0; k < 2; ++k) \
;         acc[ai][bj][m][n] = __builtin_amdgcn_mfma_f32_16x16x32_bf16(Bt[n][k], At[m][k], acc[ai][bj][m][n], 0, 0, 0); __builtin_amdgcn_s_setprio(0); } while (0)
; #define PG8_WAIT_V(n) asm volatile("s_waitcnt vmcnt(" #n ")" ::: "memory")
; #define PG8_WAIT_L(n) asm volatile("s_waitcnt lgkmcnt(" #n ")" ::: "memory")
; #define PG8_BAR __builtin_amdgcn_s_barrier()
; #define PG8_SCHED __builtin_amdgcn_sched_barrier(0)
; template <class Epi, class Sched, bool ALIGN_EPI = false, bool SP2 = false>
; __device__ __forceinline__ void gemm_phase(PG8_LAS unsigned char* lds, const Gemm g, const Sched& S, const Epi& E) {
;     ...
;         for (int t = 0; t < nt; t += 2) {
;             const bool last = (t == nt - 2);
;             const char* a1 = cA + (size_t)(t + 1) * kstepA;
;             const char* a2 = last ? nA : cA + (size_t)(t + 2) * kstepA; const char* b2 = last ? nB : cB + (size_t)(t + 2) * kstepB;
;             const char* a3 = a2 + kstepA; const char* b3 = b2 + kstepB;
;     ...
;             PG8_LDA(At, 1, 1); PG8_STAGE(PG8_SB(1, 0), b3, voffB); PG8_STAGE(PG8_SB(1, 1), b3 + hstepB, voffB); PG8_STAGE(PG8_SA(1, 0), a3, voffA);
;             PG8_WAIT_V(8); PG8_WAIT_L(0); PG8_BAR; PG8_MMA(1, 0, At, B0); PG8_MMA(1, 1, At, B1); PG8_BAR; PG8_SCHED;
	s_add_u32 s12, s74, s54
	s_addc_u32 s13, s75, 0
	s_add_i32 s26, s73, s23
	v_lshl_add_u64 v[142:143], s[12:13], 0, v[134:135]
	s_mov_b32 m0, s26
	ds_read_b128 v[180:183], v146 offset:49152
	ds_read_b128 v[184:187], v146 offset:50176
	ds_read_b128 v[188:191], v146 offset:51200
	ds_read_b128 v[192:195], v146 offset:52224
	ds_read_b128 v[196:199], v146 offset:53248
	ds_read_b128 v[200:203], v146 offset:54272
	ds_read_b128 v[204:207], v146 offset:55296
	ds_read_b128 v[222:225], v146 offset:56320
	global_load_lds_dwordx4 v[142:143], off nt
	s_add_i32 m0, s26, 0x2000
	v_lshl_add_u64 v[142:143], s[12:13], 0, v[130:131]
	s_add_u32 s12, s12, 0x4000
	s_addc_u32 s13, s13, 0
	s_add_i32 s26, s61, s23
	global_load_lds_dwordx4 v[142:143], off nt
	v_lshl_add_u64 v[142:143], s[12:13], 0, v[134:135]
	s_mov_b32 m0, s26
	s_nop 0
	global_load_lds_dwordx4 v[142:143], off nt
	v_lshl_add_u64 v[142:143], s[12:13], 0, v[130:131]
	s_add_i32 m0, s26, 0x2000
	s_nop 0
	global_load_lds_dwordx4 v[142:143], off nt
	v_lshl_add_u64 v[142:143], vcc, 0, v[136:137]
	s_mov_b32 m0, s55
	s_nop 0
	global_load_lds_dwordx4 v[142:143], off
	v_lshl_add_u64 v[142:143], vcc, 0, v[132:133]
	s_mov_b32 m0, s20
	s_nop 0
	global_load_lds_dwordx4 v[142:143], off
	s_waitcnt vmcnt(8)
	s_waitcnt lgkmcnt(0)
	s_barrier
	s_setprio 1
	s_waitcnt lgkmcnt(0)
	v_mfma_f32_16x16x32_bf16 v[62:65], v[148:151], v[180:183], v[62:65]
	v_mfma_f32_16x16x32_bf16 v[58:61], v[156:159], v[180:183], v[58:61]
	v_mfma_f32_16x16x32_bf16 v[46:49], v[148:151], v[188:191], v[46:49]
	v_mfma_f32_16x16x32_bf16 v[42:45], v[156:159], v[188:191], v[42:45]
	v_mfma_f32_16x16x32_bf16 v[30:33], v[148:151], v[196:199], v[30:33]
	v_mfma_f32_16x16x32_bf16 v[26:29], v[156:159], v[196:199], v[26:29]
	v_mfma_f32_16x16x32_bf16 v[14:17], v[148:151], v[204:207], v[14:17]
	v_mfma_f32_16x16x32_bf16 v[10:13], v[156:159], v[204:207], v[10:13]
	v_mfma_f32_16x16x32_bf16 v[62:65], v[152:155], v[184:187], v[62:65]
	v_mfma_f32_16x16x32_bf16 v[58:61], v[160:163], v[184:187], v[58:61]
	v_mfma_f32_16x16x32_bf16 v[46:49], v[152:155], v[192:195], v[46:49]
	v_mfma_f32_16x16x32_bf16 v[42:45], v[160:163], v[192:195], v[42:45]
	v_mfma_f32_16x16x32_bf16 v[30:33], v[152:155], v[200:203], v[30:33]
	v_mfma_f32_16x16x32_bf16 v[26:29], v[160:163], v[200:203], v[26:29]
	v_mfma_f32_16x16x32_bf16 v[14:17], v[152:155], v[222:225], v[14:17]
	v_mfma_f32_16x16x32_bf16 v[10:13], v[160:163], v[222:225], v[10:13]
	s_setprio 0
	s_setprio 1
	v_mfma_f32_16x16x32_bf16 v[54:57], v[164:167], v[180:183], v[54:57]
	v_mfma_f32_16x16x32_bf16 v[50:53], v[172:175], v[180:183], v[50:53]
	v_mfma_f32_16x16x32_bf16 v[38:41], v[164:167], v[188:191], v[38:41]
	v_mfma_f32_16x16x32_bf16 v[34:37], v[172:175], v[188:191], v[34:37]
	v_mfma_f32_16x16x32_bf16 v[22:25], v[164:167], v[196:199], v[22:25]
	v_mfma_f32_16x16x32_bf16 v[18:21], v[172:175], v[196:199], v[18:21]
	v_mfma_f32_16x16x32_bf16 v[6:9], v[164:167], v[204:207], v[6:9]
	v_mfma_f32_16x16x32_bf16 v[2:5], v[172:175], v[204:207], v[2:5]
	v_mfma_f32_16x16x32_bf16 v[54:57], v[168:171], v[184:187], v[54:57]
	v_mfma_f32_16x16x32_bf16 v[50:53], v[176:179], v[184:187], v[50:53]
	v_mfma_f32_16x16x32_bf16 v[38:41], v[168:171], v[192:195], v[38:41]
	v_mfma_f32_16x16x32_bf16 v[34:37], v[176:179], v[192:195], v[34:37]
	v_mfma_f32_16x16x32_bf16 v[22:25], v[168:171], v[200:203], v[22:25]
	v_mfma_f32_16x16x32_bf16 v[18:21], v[176:179], v[200:203], v[18:21]
	v_mfma_f32_16x16x32_bf16 v[6:9], v[168:171], v[222:225], v[6:9]
	v_mfma_f32_16x16x32_bf16 v[2:5], v[176:179], v[222:225], v[2:5]
	s_setprio 0
	s_barrier
	s_add_u32 s76, s76, s58
	s_addc_u32 s77, s77, 0
	s_add_u32 s6, s6, 0x400000
	s_addc_u32 s7, s7, 0
	s_cmp_ge_u32 s71, s25
	s_cbranch_scc1 .LBB0_375
